# GEMM ping-pong roles swapped: waves 4-7 are the leading group, waves 0-3 lag by one barrier (age-arbitration pairing test)
# speedup vs baseline: 1.0081x; 1.0040x over previous
.LBB0_10:
	v_sub_co_u32_e64 v0, s[76:77], s22, 19
	s_and_b64 s[4:5], s[76:77], exec
	v_readfirstlane_b32 s4, v0
	s_cselect_b32 s60, s22, s4
	s_mov_b64 s[26:27], -1
	s_mov_b64 s[28:29], 0
	s_cmp_lt_i32 s60, 11
	s_mov_b64 s[4:5], 0
	s_cbranch_scc1 .LBB0_232
	s_cmp_gt_i32 s60, 14
	s_cbranch_scc0 .LBB0_125
	s_cmp_gt_i32 s60, 16
	s_cbranch_scc0 .LBB0_85
	s_cmp_gt_i32 s60, 17
	s_cbranch_scc0 .LBB0_52
	s_mov_b64 s[4:5], -1
	s_mov_b64 s[26:27], 0
	s_cmp_eq_u32 s60, 18
	s_cbranch_scc0 .LBB0_52
	v_readlane_b32 s10, v252, 17
	s_mov_b64 s[34:35], s[0:1]
	s_mov_b64 s[38:39], s[0:1]
	s_mov_b64 s[4:5], s[0:1]
	s_mov_b64 s[28:29], s[0:1]
	s_mov_b64 s[30:31], s[0:1]
	v_mov_b32_e32 v8, v186
	v_readlane_b32 s11, v252, 18
	s_andn2_b64 vcc, exec, s[10:11]
	v_readfirstlane_b32 s9, v8
	s_cbranch_vccnz .LBB0_51
	v_lshlrev_b32_e32 v0, 4, v8
	s_waitcnt lgkmcnt(0)
	v_add_u32_e32 v1, 0x2000, v0
	v_ashrrev_i32_e32 v2, 31, v1
	v_lshrrev_b32_e32 v2, 22, v2
	v_add_u32_e32 v2, v1, v2
	v_ashrrev_i32_e32 v9, 10, v2
	v_mul_i32_i24_e32 v2, 0x400, v9
	v_sub_u32_e32 v1, v1, v2
	v_lshrrev_b32_e32 v2, 4, v1
	v_bitop3_b32 v1, v2, v1, 32 bitop3:0x6c
	v_ashrrev_i32_e32 v2, 31, v1
	v_lshrrev_b32_e32 v2, 26, v2
	v_add_u32_e32 v2, v1, v2
	v_lshlrev_b32_e32 v3, 3, v9
	v_ashrrev_i32_e32 v10, 6, v2
	v_and_b32_e32 v3, -16, v3
	v_add_u32_e32 v3, v10, v3
	s_load_dwordx2 s[10:11], s[34:35], 0xf8
	s_nop 0
	s_load_dwordx2 s[34:35], s[38:39], 0xf8
	v_and_b32_e32 v4, 3, v10
	s_mov_b32 s12, 0xffffe0
	v_lshrrev_b32_e32 v5, 2, v3
	v_lshlrev_b32_e32 v6, 1, v3
	v_and_or_b32 v4, v3, s12, v4
	v_and_b32_e32 v5, 4, v5
	v_and_b32_e32 v6, 24, v6
	v_or3_b32 v4, v4, v5, v6
	v_lshlrev_b32_e32 v5, 5, v9
	v_and_b32_e32 v2, 0xc0, v2
	v_and_b32_e32 v11, 32, v5
	v_sub_u32_e32 v1, v1, v2
	v_mov_b32_e32 v5, 1
	s_waitcnt lgkmcnt(0)
	s_add_u32 s33, s10, 0x3290000
	v_ashrrev_i16_sdwa v1, v5, sext(v1) dst_sel:DWORD dst_unused:UNUSED_PAD src0_sel:DWORD src1_sel:BYTE_0
	s_addc_u32 s41, s11, 0
	v_bfe_i32 v12, v1, 0, 16
	s_movk_i32 s11, 0xb00
	v_mul_u32_u24_e32 v4, 0xb00, v4
	v_add_u32_e32 v1, v11, v12
	v_mul_lo_u32 v2, v3, s11
	v_add_lshl_u32 v150, v4, v1, 1
	v_add_lshl_u32 v152, v1, v2, 1
	v_bfe_i32 v1, v8, 27, 1
	v_lshrrev_b32_e32 v1, 22, v1
	v_add_u32_e32 v1, v0, v1
	v_and_b32_e32 v1, 0xfffffc00, v1
	v_sub_u32_e32 v0, v0, v1
	v_lshrrev_b32_e32 v1, 4, v0
	v_bitop3_b32 v1, v1, v0, 32 bitop3:0x6c
	v_ashrrev_i32_e32 v0, 31, v0
	v_lshrrev_b32_e32 v0, 26, v0
	v_add_u32_e32 v0, v1, v0
	v_ashrrev_i32_e32 v13, 6, v0
	v_ashrrev_i32_e32 v0, 31, v8
	v_lshrrev_b32_e32 v0, 26, v0
	v_add_u32_e32 v0, v8, v0
	v_ashrrev_i32_e32 v14, 6, v0
	v_lshlrev_b32_e32 v0, 3, v14
	v_and_b32_e32 v0, -16, v0
	v_add_u32_e32 v0, v13, v0
	v_and_b32_e32 v2, 3, v13
	v_lshrrev_b32_e32 v3, 2, v0
	v_lshlrev_b32_e32 v4, 1, v0
	v_and_or_b32 v2, v0, s12, v2
	v_and_b32_e32 v3, 4, v3
	v_and_b32_e32 v4, 24, v4
	v_or3_b32 v2, v2, v3, v4
	v_lshlrev_b32_e32 v3, 5, v14
	s_add_u32 s54, s34, 0x2d00000
	v_and_b32_e32 v15, 32, v3
	v_mul_i32_i24_e32 v3, 64, v13
	s_addc_u32 s55, s35, 0
	s_ashr_i32 s10, s9, 6
	v_sub_u32_e32 v1, v1, v3
	s_ashr_i32 s6, s9, 8
	s_lshl_b32 s57, s10, 10
	v_ashrrev_i16_sdwa v1, v5, sext(v1) dst_sel:DWORD dst_unused:UNUSED_PAD src0_sel:DWORD src1_sel:BYTE_0
	v_mul_lo_u32 v0, v0, s11
	v_readlane_b32 s11, v254, 53
	v_bfe_i32 v16, v1, 0, 16
	s_add_u32 s52, s54, s11
	v_readlane_b32 s11, v254, 51
	v_mul_u32_u24_e32 v2, 0xb00, v2
	v_add_u32_e32 v1, v15, v16
	s_addc_u32 s53, s55, s11
	s_add_i32 s58, s57, 0
	v_add_lshl_u32 v140, v2, v1, 1
	s_add_i32 m0, s58, 0x10000
	v_readlane_b32 s11, v254, 57
	global_load_lds_dwordx4 v140, s[52:53]
	s_add_i32 m0, s58, 0x12000
	s_add_u32 s50, s33, s11
	v_readlane_b32 s11, v254, 54
	v_add_lshl_u32 v154, v1, v0, 1
	global_load_lds_dwordx4 v150, s[52:53]
	s_addc_u32 s51, s41, s11
	s_mov_b32 m0, s58
	s_add_i32 s59, s58, 0x2000
	global_load_lds_dwordx4 v154, s[50:51]
	s_mov_b32 m0, s59
	s_add_u32 s34, s52, 0xb0000
	global_load_lds_dwordx4 v152, s[50:51]
	s_addc_u32 s35, s53, 0
	s_add_i32 m0, s58, 0x14000
	v_mov_b32_e32 v151, v141
	global_load_lds_dwordx4 v140, s[34:35]
	s_add_i32 m0, s58, 0x16000
	v_mov_b32_e32 v155, v141
	global_load_lds_dwordx4 v150, s[34:35]
	s_add_u32 s34, s50, 0xb0000
	s_addc_u32 s35, s51, 0
	s_add_i32 s68, s58, 0x4000
	s_mov_b32 m0, s68
	s_add_i32 s69, s58, 0x6000
	global_load_lds_dwordx4 v154, s[34:35]
	s_mov_b32 m0, s69
	v_mov_b32_e32 v153, v141
	global_load_lds_dwordx4 v152, s[34:35]
	s_load_dwordx2 s[4:5], s[4:5], 0xf8
	s_nop 0
	s_load_dwordx2 s[34:35], s[28:29], 0xf8
	s_nop 0
	s_load_dwordx2 s[28:29], s[30:31], 0xf8
	v_lshl_add_u64 v[6:7], s[52:53], 0, v[140:141]
	v_lshl_add_u64 v[4:5], s[52:53], 0, v[150:151]
	v_lshl_add_u64 v[2:3], s[50:51], 0, v[154:155]
	s_cmp_lg_u32 s6, 0
	v_lshl_add_u64 v[0:1], s[50:51], 0, v[152:153]
	s_cbranch_scc1 .LBB0_18
	s_barrier

.LBB0_48:
	s_waitcnt vmcnt(0)
	s_cmpk_lt_u32 s9, 0x100
	s_cbranch_scc1 .LBB0_50
	s_barrier

my_rs0_7:
	s_or_b64 exec, exec, s[38:39]
	v_readlane_b32 s10, v252, 21
	v_readlane_b32 s11, v252, 22
	s_andn2_b64 vcc, exec, s[10:11]
	s_waitcnt lgkmcnt(0)
	s_barrier
	s_cbranch_vccnz .LBB0_83
	v_ashrrev_i32_e32 v1, 31, v8
	v_lshrrev_b32_e32 v1, 26, v1
	v_add_u32_e32 v1, v8, v1
	v_ashrrev_i32_e32 v9, 6, v1
	v_bfe_i32 v1, v8, 27, 1
	v_lshlrev_b32_e32 v0, 4, v8
	v_lshrrev_b32_e32 v1, 22, v1
	v_add_u32_e32 v1, v0, v1
	v_and_b32_e32 v1, 0xfffffc00, v1
	v_sub_u32_e32 v1, v0, v1
	v_lshrrev_b32_e32 v2, 4, v1
	v_bitop3_b32 v2, v2, v1, 32 bitop3:0x6c
	v_ashrrev_i32_e32 v1, 31, v1
	v_lshrrev_b32_e32 v1, 26, v1
	v_add_u32_e32 v1, v2, v1
	v_ashrrev_i32_e32 v10, 6, v1
	v_lshlrev_b32_e32 v3, 3, v9
	v_mul_i32_i24_e32 v4, 64, v10
	v_and_b32_e32 v3, -16, v3
	v_sub_u32_e32 v2, v2, v4
	v_mov_b32_e32 v6, 1
	v_add_u32_e32 v1, v10, v3
	v_lshlrev_b32_e32 v3, 5, v9
	v_ashrrev_i16_sdwa v2, v6, sext(v2) dst_sel:DWORD dst_unused:UNUSED_PAD src0_sel:DWORD src1_sel:BYTE_0
	v_and_b32_e32 v3, 32, v3
	v_bfe_i32 v11, v2, 0, 16
	v_and_b32_e32 v5, 3, v10
	s_mov_b32 s10, 0x1fffe0
	v_add_lshl_u32 v3, v3, v11, 1
	v_add_u32_e32 v0, 0x2000, v0
	v_lshlrev_b32_e32 v2, 1, v1
	v_lshrrev_b32_e32 v4, 2, v1
	v_and_or_b32 v5, v1, s10, v5
	v_lshl_add_u32 v128, v1, 11, v3
	v_ashrrev_i32_e32 v1, 31, v0
	v_lshrrev_b32_e32 v1, 22, v1
	v_add_u32_e32 v1, v0, v1
	v_ashrrev_i32_e32 v12, 10, v1
	v_mul_i32_i24_e32 v1, 0x400, v12
	v_sub_u32_e32 v0, v0, v1
	v_and_b32_e32 v2, 24, v2
	v_and_b32_e32 v4, 4, v4
	v_lshrrev_b32_e32 v1, 4, v0
	v_or3_b32 v2, v5, v4, v2
	v_bitop3_b32 v0, v1, v0, 32 bitop3:0x6c
	v_lshl_add_u32 v140, v2, 11, v3
	v_ashrrev_i32_e32 v2, 31, v0
	v_lshrrev_b32_e32 v2, 26, v2
	s_add_u32 s33, s34, 0x12290000
	v_lshlrev_b32_e32 v1, 3, v12
	v_add_u32_e32 v2, v0, v2
	s_addc_u32 s41, s35, 0
	v_and_b32_e32 v1, -16, v1
	v_ashrrev_i32_e32 v13, 6, v2
	s_add_u32 s57, s30, 0x2200000
	v_add_u32_e32 v1, v13, v1
	v_and_b32_e32 v4, 3, v13
	s_addc_u32 s58, s31, 0
	v_and_b32_e32 v2, 0xc0, v2
	v_and_or_b32 v4, v1, s10, v4
	s_ashr_i32 s10, s9, 6
	s_ashr_i32 s6, s9, 8
	v_sub_u32_e32 v0, v0, v2
	s_lshl_b32 s59, s10, 10
	v_readlane_b32 s26, v253, 50
	v_ashrrev_i16_sdwa v0, v6, sext(v0) dst_sel:DWORD dst_unused:UNUSED_PAD src0_sel:DWORD src1_sel:BYTE_0
	v_readlane_b32 s27, v253, 51
	s_add_u32 s50, s57, s26
	v_lshlrev_b32_e32 v3, 5, v12
	v_bfe_i32 v14, v0, 0, 16
	v_lshlrev_b32_e32 v0, 1, v1
	v_lshrrev_b32_e32 v2, 2, v1
	s_addc_u32 s51, s58, s27
	s_add_i32 s68, s59, 0
	v_and_b32_e32 v3, 32, v3
	v_and_b32_e32 v0, 24, v0
	v_and_b32_e32 v2, 4, v2
	s_add_i32 m0, s68, 0x10000
	v_or3_b32 v0, v4, v2, v0
	v_add_lshl_u32 v2, v3, v14, 1
	global_load_lds_dwordx4 v140, s[50:51]
	s_add_i32 m0, s68, 0x12000
	v_readlane_b32 s26, v254, 2
	v_lshl_add_u32 v132, v0, 11, v2
	v_readlane_b32 s27, v254, 3
	s_add_u32 s26, s33, s26
	global_load_lds_dwordx4 v132, s[50:51]
	s_addc_u32 s27, s41, s27
	s_mov_b32 m0, s68
	s_add_i32 s69, s68, 0x2000
	v_lshl_add_u32 v130, v1, 11, v2
	global_load_lds_dwordx4 v128, s[26:27]
	s_mov_b32 m0, s69
	s_add_u32 s30, s50, 0x40000
	global_load_lds_dwordx4 v130, s[26:27]
	s_addc_u32 s31, s51, 0
	s_add_i32 m0, s68, 0x14000
	v_mov_b32_e32 v133, v141
	global_load_lds_dwordx4 v140, s[30:31]
	s_add_i32 m0, s68, 0x16000
	v_mov_b32_e32 v129, v141
	global_load_lds_dwordx4 v132, s[30:31]
	s_add_u32 s30, s26, 0x40000
	s_addc_u32 s31, s27, 0
	s_add_i32 s70, s68, 0x4000
	s_mov_b32 m0, s70
	s_add_i32 s71, s68, 0x6000
	global_load_lds_dwordx4 v128, s[30:31]
	s_mov_b32 m0, s71
	v_mov_b32_e32 v131, v141
	global_load_lds_dwordx4 v130, s[30:31]
	v_lshl_add_u64 v[6:7], s[50:51], 0, v[140:141]
	v_lshl_add_u64 v[4:5], s[50:51], 0, v[132:133]
	v_lshl_add_u64 v[2:3], s[26:27], 0, v[128:129]
	s_cmp_lg_u32 s6, 0
	v_lshl_add_u64 v[0:1], s[26:27], 0, v[130:131]
	s_cbranch_scc1 .LBB0_72
	s_barrier

.LBB0_85:
	s_and_b64 vcc, exec, s[26:27]
	s_cbranch_vccz .LBB0_124
	s_cmp_lt_i32 s60, 16
	s_cbranch_scc0 .LBB0_124
	v_readlane_b32 s10, v252, 17
	s_mov_b64 s[38:39], s[0:1]
	s_mov_b64 s[34:35], s[0:1]
	s_mov_b64 s[26:27], s[0:1]
	s_mov_b64 s[28:29], s[0:1]
	s_mov_b64 s[30:31], s[0:1]
	v_mov_b32_e32 v8, v186
	v_readlane_b32 s11, v252, 18
	s_andn2_b64 vcc, exec, s[10:11]
	v_readfirstlane_b32 s9, v8
	s_cbranch_vccnz .LBB0_123
	v_lshlrev_b32_e32 v0, 4, v8
	s_waitcnt lgkmcnt(0)
	v_add_u32_e32 v1, 0x2000, v0
	v_ashrrev_i32_e32 v2, 31, v1
	v_lshrrev_b32_e32 v2, 22, v2
	v_add_u32_e32 v2, v1, v2
	v_ashrrev_i32_e32 v9, 10, v2
	v_mul_i32_i24_e32 v2, 0x400, v9
	v_sub_u32_e32 v1, v1, v2
	v_lshrrev_b32_e32 v2, 4, v1
	v_bitop3_b32 v1, v2, v1, 32 bitop3:0x6c
	s_load_dwordx2 s[10:11], s[38:39], 0xf8
	s_nop 0
	s_load_dwordx2 s[34:35], s[34:35], 0xf8
	v_ashrrev_i32_e32 v2, 31, v1
	v_lshrrev_b32_e32 v2, 26, v2
	v_add_u32_e32 v2, v1, v2
	v_lshlrev_b32_e32 v3, 3, v9
	v_ashrrev_i32_e32 v10, 6, v2
	v_and_b32_e32 v3, -16, v3
	s_waitcnt lgkmcnt(0)
	s_add_u32 s33, s10, 0xb290000
	v_add_u32_e32 v3, v10, v3
	s_addc_u32 s41, s11, 0
	v_and_b32_e32 v4, 3, v10
	s_mov_b32 s11, 0x1fffe0
	v_lshrrev_b32_e32 v5, 2, v3
	v_lshlrev_b32_e32 v6, 1, v3
	v_and_or_b32 v4, v3, s11, v4
	v_and_b32_e32 v5, 4, v5
	v_and_b32_e32 v6, 24, v6
	v_and_b32_e32 v2, 0xc0, v2
	v_or3_b32 v4, v4, v5, v6
	v_sub_u32_e32 v1, v1, v2
	v_mov_b32_e32 v6, 1
	v_lshlrev_b32_e32 v5, 5, v9
	v_ashrrev_i16_sdwa v1, v6, sext(v1) dst_sel:DWORD dst_unused:UNUSED_PAD src0_sel:DWORD src1_sel:BYTE_0
	v_and_b32_e32 v5, 32, v5
	v_bfe_i32 v11, v1, 0, 16
	v_add_lshl_u32 v1, v5, v11, 1
	v_lshl_add_u32 v150, v4, 11, v1
	v_lshl_add_u32 v152, v3, 11, v1
	v_bfe_i32 v1, v8, 27, 1
	v_lshrrev_b32_e32 v1, 22, v1
	v_add_u32_e32 v1, v0, v1
	v_and_b32_e32 v1, 0xfffffc00, v1
	v_sub_u32_e32 v0, v0, v1
	v_lshrrev_b32_e32 v1, 4, v0
	v_bitop3_b32 v1, v1, v0, 32 bitop3:0x6c
	v_ashrrev_i32_e32 v0, 31, v0
	v_lshrrev_b32_e32 v0, 26, v0
	v_add_u32_e32 v0, v1, v0
	v_ashrrev_i32_e32 v12, 6, v0
	v_ashrrev_i32_e32 v0, 31, v8
	v_lshrrev_b32_e32 v0, 26, v0
	v_add_u32_e32 v0, v8, v0
	v_ashrrev_i32_e32 v13, 6, v0
	v_lshlrev_b32_e32 v0, 3, v13
	v_and_b32_e32 v0, -16, v0
	v_add_u32_e32 v0, v12, v0
	s_add_u32 s57, s34, 0x1eb14000
	v_and_b32_e32 v2, 3, v12
	v_lshrrev_b32_e32 v3, 2, v0
	v_lshlrev_b32_e32 v4, 1, v0
	s_addc_u32 s70, s35, 0
	s_ashr_i32 s10, s9, 6
	v_and_or_b32 v2, v0, s11, v2
	v_and_b32_e32 v3, 4, v3
	v_and_b32_e32 v4, 24, v4
	s_ashr_i32 s6, s9, 8
	s_lshl_b32 s71, s10, 10
	v_or3_b32 v2, v2, v3, v4
	v_mul_i32_i24_e32 v4, 64, v12
	v_readlane_b32 s34, v254, 8
	v_sub_u32_e32 v1, v1, v4
	v_readlane_b32 s35, v254, 9
	s_add_u32 s11, s57, s34
	v_lshlrev_b32_e32 v3, 5, v13
	v_ashrrev_i16_sdwa v1, v6, sext(v1) dst_sel:DWORD dst_unused:UNUSED_PAD src0_sel:DWORD src1_sel:BYTE_0
	s_addc_u32 s12, s70, s35
	v_readlane_b32 s34, v253, 56
	v_and_b32_e32 v3, 32, v3
	v_bfe_i32 v14, v1, 0, 16
	v_readlane_b32 s35, v253, 57
	s_add_u32 s58, s11, s34
	v_add_lshl_u32 v1, v3, v14, 1
	s_addc_u32 s59, s12, s35
	s_add_i32 s72, s71, 0
	v_lshl_add_u32 v140, v2, 11, v1
	s_add_i32 m0, s72, 0x10000
	v_readlane_b32 s34, v254, 12
	global_load_lds_dwordx4 v140, s[58:59]
	s_add_i32 m0, s72, 0x12000
	v_readlane_b32 s35, v254, 13
	s_add_u32 s11, s33, s34
	s_addc_u32 s12, s41, s35
	v_readlane_b32 s34, v254, 16
	v_readlane_b32 s35, v254, 17
	s_add_u32 s54, s11, s34
	v_lshl_add_u32 v154, v0, 11, v1
	global_load_lds_dwordx4 v150, s[58:59]
	s_addc_u32 s55, s12, s35
	s_mov_b32 m0, s72
	s_add_i32 s73, s72, 0x2000
	global_load_lds_dwordx4 v154, s[54:55]
	s_mov_b32 m0, s73
	s_add_u32 s34, s58, 0x40000
	global_load_lds_dwordx4 v152, s[54:55]
	s_addc_u32 s35, s59, 0
	s_add_i32 m0, s72, 0x14000
	v_mov_b32_e32 v151, v141
	global_load_lds_dwordx4 v140, s[34:35]
	s_add_i32 m0, s72, 0x16000
	v_mov_b32_e32 v155, v141
	global_load_lds_dwordx4 v150, s[34:35]
	s_add_u32 s34, s54, 0x40000
	s_addc_u32 s35, s55, 0
	s_add_i32 s74, s72, 0x4000
	s_mov_b32 m0, s74
	s_add_i32 s75, s72, 0x6000
	global_load_lds_dwordx4 v154, s[34:35]
	s_mov_b32 m0, s75
	v_mov_b32_e32 v153, v141
	global_load_lds_dwordx4 v152, s[34:35]
	s_load_dwordx2 s[26:27], s[26:27], 0xf8
	s_nop 0
	s_load_dwordx2 s[34:35], s[28:29], 0xf8
	s_nop 0
	s_load_dwordx2 s[28:29], s[30:31], 0xf8
	v_lshl_add_u64 v[6:7], s[58:59], 0, v[140:141]
	v_lshl_add_u64 v[4:5], s[58:59], 0, v[150:151]
	v_lshl_add_u64 v[2:3], s[54:55], 0, v[154:155]
	s_cmp_lg_u32 s6, 0
	v_lshl_add_u64 v[0:1], s[54:55], 0, v[152:153]
	s_cbranch_scc1 .LBB0_90
	s_barrier

.LBB0_176:
	s_or_b64 exec, exec, s[38:39]
	v_readlane_b32 s10, v252, 17
	v_readlane_b32 s11, v252, 18
	s_andn2_b64 vcc, exec, s[10:11]
	s_waitcnt vmcnt(0) lgkmcnt(0)
	s_barrier
	s_cbranch_vccnz .LBB0_230
	v_ashrrev_i32_e32 v1, 31, v8
	v_lshrrev_b32_e32 v1, 26, v1
	v_add_u32_e32 v1, v8, v1
	v_ashrrev_i32_e32 v9, 6, v1
	v_bfe_i32 v1, v8, 27, 1
	v_lshlrev_b32_e32 v0, 4, v8
	v_lshrrev_b32_e32 v1, 22, v1
	v_add_u32_e32 v1, v0, v1
	v_and_b32_e32 v1, 0xfffffc00, v1
	v_sub_u32_e32 v1, v0, v1
	v_lshrrev_b32_e32 v2, 4, v1
	v_bitop3_b32 v2, v2, v1, 32 bitop3:0x6c
	v_ashrrev_i32_e32 v1, 31, v1
	v_lshrrev_b32_e32 v1, 26, v1
	v_add_u32_e32 v1, v2, v1
	v_ashrrev_i32_e32 v10, 6, v1
	v_lshlrev_b32_e32 v3, 3, v9
	v_mul_i32_i24_e32 v4, 64, v10
	v_and_b32_e32 v3, -16, v3
	v_sub_u32_e32 v2, v2, v4
	v_mov_b32_e32 v6, 1
	v_add_u32_e32 v1, v10, v3
	v_lshlrev_b32_e32 v3, 5, v9
	v_ashrrev_i16_sdwa v2, v6, sext(v2) dst_sel:DWORD dst_unused:UNUSED_PAD src0_sel:DWORD src1_sel:BYTE_0
	v_and_b32_e32 v3, 32, v3
	v_bfe_i32 v11, v2, 0, 16
	v_and_b32_e32 v5, 3, v10
	s_mov_b32 s10, 0x1fffe0
	v_add_lshl_u32 v3, v3, v11, 1
	v_add_u32_e32 v0, 0x2000, v0
	v_lshlrev_b32_e32 v2, 1, v1
	v_lshrrev_b32_e32 v4, 2, v1
	v_and_or_b32 v5, v1, s10, v5
	v_lshl_add_u32 v128, v1, 11, v3
	v_ashrrev_i32_e32 v1, 31, v0
	v_lshrrev_b32_e32 v1, 22, v1
	v_add_u32_e32 v1, v0, v1
	v_ashrrev_i32_e32 v12, 10, v1
	v_mul_i32_i24_e32 v1, 0x400, v12
	v_sub_u32_e32 v0, v0, v1
	v_and_b32_e32 v2, 24, v2
	v_and_b32_e32 v4, 4, v4
	v_lshrrev_b32_e32 v1, 4, v0
	v_or3_b32 v2, v5, v4, v2
	v_bitop3_b32 v0, v1, v0, 32 bitop3:0x6c
	v_lshl_add_u32 v130, v2, 11, v3
	v_ashrrev_i32_e32 v2, 31, v0
	s_add_u32 s33, s26, 0x12290000
	v_lshrrev_b32_e32 v2, 26, v2
	s_addc_u32 s41, s27, 0
	v_lshlrev_b32_e32 v1, 3, v12
	v_add_u32_e32 v2, v0, v2
	s_add_u32 s57, s30, 0x1e314000
	v_and_b32_e32 v1, -16, v1
	v_ashrrev_i32_e32 v13, 6, v2
	s_addc_u32 s70, s31, 0
	s_ashr_i32 s6, s9, 6
	v_add_u32_e32 v1, v13, v1
	v_and_b32_e32 v4, 3, v13
	v_and_or_b32 v4, v1, s10, v4
	s_ashr_i32 s10, s9, 8
	s_lshl_b32 s71, s6, 10
	v_readlane_b32 s26, v254, 8
	v_readlane_b32 s27, v254, 9
	s_add_u32 s11, s57, s26
	s_addc_u32 s12, s70, s27
	v_readlane_b32 s26, v253, 56
	v_and_b32_e32 v2, 0xc0, v2
	v_readlane_b32 s27, v253, 57
	s_add_u32 s54, s11, s26
	v_sub_u32_e32 v0, v0, v2
	s_addc_u32 s55, s12, s27
	s_add_i32 s72, s71, 0
	v_ashrrev_i16_sdwa v0, v6, sext(v0) dst_sel:DWORD dst_unused:UNUSED_PAD src0_sel:DWORD src1_sel:BYTE_0
	s_add_i32 m0, s72, 0x10000
	v_lshlrev_b32_e32 v3, 5, v12
	v_bfe_i32 v14, v0, 0, 16
	v_lshlrev_b32_e32 v0, 1, v1
	v_lshrrev_b32_e32 v2, 2, v1
	global_load_lds_dwordx4 v130, s[54:55]
	s_add_i32 m0, s72, 0x12000
	v_readlane_b32 s26, v254, 12
	v_and_b32_e32 v3, 32, v3
	v_and_b32_e32 v0, 24, v0
	v_and_b32_e32 v2, 4, v2
	v_readlane_b32 s27, v254, 13
	s_add_u32 s11, s33, s26
	v_or3_b32 v0, v4, v2, v0
	v_add_lshl_u32 v2, v3, v14, 1
	s_addc_u32 s12, s41, s27
	v_readlane_b32 s26, v254, 16
	v_lshl_add_u32 v134, v0, 11, v2
	v_readlane_b32 s27, v254, 17
	s_add_u32 s26, s11, s26
	global_load_lds_dwordx4 v134, s[54:55]
	s_addc_u32 s27, s12, s27
	s_mov_b32 m0, s72
	s_add_i32 s73, s72, 0x2000
	v_lshl_add_u32 v132, v1, 11, v2
	global_load_lds_dwordx4 v128, s[26:27]
	s_mov_b32 m0, s73
	s_add_u32 s30, s54, 0x40000
	global_load_lds_dwordx4 v132, s[26:27]
	s_addc_u32 s31, s55, 0
	s_add_i32 m0, s72, 0x14000
	v_mov_b32_e32 v131, v141
	global_load_lds_dwordx4 v130, s[30:31]
	s_add_i32 m0, s72, 0x16000
	v_mov_b32_e32 v135, v141
	global_load_lds_dwordx4 v134, s[30:31]
	s_add_u32 s30, s26, 0x40000
	s_addc_u32 s31, s27, 0
	s_add_i32 s74, s72, 0x4000
	s_mov_b32 m0, s74
	s_add_i32 s75, s72, 0x6000
	global_load_lds_dwordx4 v128, s[30:31]
	s_mov_b32 m0, s75
	v_mov_b32_e32 v129, v141
	global_load_lds_dwordx4 v132, s[30:31]
	v_mov_b32_e32 v133, v141
	v_lshl_add_u64 v[6:7], s[54:55], 0, v[130:131]
	v_lshl_add_u64 v[4:5], s[54:55], 0, v[134:135]
	v_lshl_add_u64 v[2:3], s[26:27], 0, v[128:129]
	s_cmp_lg_u32 s10, 0
	v_lshl_add_u64 v[0:1], s[26:27], 0, v[132:133]
	s_cbranch_scc1 .LBB0_179
	s_barrier

.LBB0_232:
	s_and_b64 vcc, exec, s[26:27]
	s_cbranch_vccz .LBB0_444
	s_cmp_gt_i32 s60, 3
	s_mov_b64 s[26:27], -1
	s_cbranch_scc0 .LBB0_359
	s_cmp_gt_i32 s60, 5
	s_cbranch_scc0 .LBB0_323
	s_cmp_gt_i32 s60, 9
	s_cbranch_scc0 .LBB0_269
	v_readlane_b32 s10, v252, 17
	s_mov_b64 s[26:27], s[0:1]
	s_mov_b64 s[38:39], s[0:1]
	s_mov_b64 s[28:29], s[0:1]
	s_mov_b64 s[30:31], s[0:1]
	s_mov_b64 s[34:35], s[0:1]
	v_mov_b32_e32 v8, v186
	v_readlane_b32 s11, v252, 18
	s_andn2_b64 vcc, exec, s[10:11]
	v_readfirstlane_b32 s9, v8
	s_cbranch_vccnz .LBB0_268
	v_lshlrev_b32_e32 v0, 4, v8
	s_waitcnt lgkmcnt(0)
	v_add_u32_e32 v1, 0x2000, v0
	v_ashrrev_i32_e32 v2, 31, v1
	v_lshrrev_b32_e32 v2, 22, v2
	v_add_u32_e32 v2, v1, v2
	v_ashrrev_i32_e32 v9, 10, v2
	v_mul_i32_i24_e32 v2, 0x400, v9
	v_sub_u32_e32 v1, v1, v2
	v_lshrrev_b32_e32 v2, 4, v1
	v_bitop3_b32 v1, v2, v1, 32 bitop3:0x6c
	s_load_dwordx2 s[10:11], s[38:39], 0xf8
	s_nop 0
	s_load_dwordx2 s[26:27], s[26:27], 0xf0
	v_ashrrev_i32_e32 v2, 31, v1
	v_lshrrev_b32_e32 v2, 26, v2
	v_add_u32_e32 v2, v1, v2
	v_lshlrev_b32_e32 v3, 3, v9
	v_ashrrev_i32_e32 v10, 6, v2
	v_and_b32_e32 v3, -16, v3
	s_waitcnt lgkmcnt(0)
	s_add_u32 s33, s10, 0x1800000
	v_add_u32_e32 v3, v10, v3
	s_addc_u32 s41, s11, 0
	v_and_b32_e32 v4, 3, v10
	s_mov_b32 s11, 0x1fffe0
	v_lshrrev_b32_e32 v5, 2, v3
	v_lshlrev_b32_e32 v6, 1, v3
	v_and_or_b32 v4, v3, s11, v4
	v_and_b32_e32 v5, 4, v5
	v_and_b32_e32 v6, 24, v6
	v_and_b32_e32 v2, 0xc0, v2
	v_or3_b32 v4, v4, v5, v6
	v_sub_u32_e32 v1, v1, v2
	v_mov_b32_e32 v6, 1
	v_lshlrev_b32_e32 v5, 5, v9
	v_ashrrev_i16_sdwa v1, v6, sext(v1) dst_sel:DWORD dst_unused:UNUSED_PAD src0_sel:DWORD src1_sel:BYTE_0
	v_and_b32_e32 v5, 32, v5
	v_bfe_i32 v11, v1, 0, 16
	v_add_lshl_u32 v1, v5, v11, 1
	v_lshl_add_u32 v150, v4, 11, v1
	v_lshl_add_u32 v152, v3, 11, v1
	v_bfe_i32 v1, v8, 27, 1
	v_lshrrev_b32_e32 v1, 22, v1
	v_add_u32_e32 v1, v0, v1
	v_and_b32_e32 v1, 0xfffffc00, v1
	v_sub_u32_e32 v0, v0, v1
	v_lshrrev_b32_e32 v1, 4, v0
	v_bitop3_b32 v1, v1, v0, 32 bitop3:0x6c
	v_ashrrev_i32_e32 v0, 31, v0
	v_lshrrev_b32_e32 v0, 26, v0
	v_add_u32_e32 v0, v1, v0
	v_ashrrev_i32_e32 v12, 6, v0
	v_ashrrev_i32_e32 v0, 31, v8
	v_lshrrev_b32_e32 v0, 26, v0
	v_add_u32_e32 v0, v8, v0
	v_ashrrev_i32_e32 v13, 6, v0
	v_lshlrev_b32_e32 v0, 3, v13
	v_and_b32_e32 v0, -16, v0
	v_add_u32_e32 v0, v12, v0
	v_and_b32_e32 v2, 3, v12
	v_lshrrev_b32_e32 v3, 2, v0
	v_lshlrev_b32_e32 v4, 1, v0
	v_and_or_b32 v2, v0, s11, v2
	v_and_b32_e32 v3, 4, v3
	v_and_b32_e32 v4, 24, v4
	v_or3_b32 v2, v2, v3, v4
	v_mul_i32_i24_e32 v4, 64, v12
	s_ashr_i32 s10, s9, 6
	v_sub_u32_e32 v1, v1, v4
	s_ashr_i32 s6, s9, 8
	s_lshl_b32 s57, s10, 10
	v_lshlrev_b32_e32 v3, 5, v13
	v_ashrrev_i16_sdwa v1, v6, sext(v1) dst_sel:DWORD dst_unused:UNUSED_PAD src0_sel:DWORD src1_sel:BYTE_0
	v_readlane_b32 s38, v253, 58
	v_and_b32_e32 v3, 32, v3
	v_bfe_i32 v14, v1, 0, 16
	v_readlane_b32 s39, v253, 59
	s_add_u32 s54, s33, s38
	v_add_lshl_u32 v1, v3, v14, 1
	s_addc_u32 s55, s41, s39
	s_add_i32 s68, s57, 0
	v_lshl_add_u32 v140, v2, 11, v1
	s_add_i32 m0, s68, 0x10000
	v_readlane_b32 s38, v254, 18
	global_load_lds_dwordx4 v140, s[54:55]
	s_add_i32 m0, s68, 0x12000
	v_readlane_b32 s39, v254, 19
	s_add_u32 s52, s26, s38
	v_lshl_add_u32 v154, v0, 11, v1
	global_load_lds_dwordx4 v150, s[54:55]
	s_addc_u32 s53, s27, s39
	s_mov_b32 m0, s68
	s_add_i32 s69, s68, 0x2000
	global_load_lds_dwordx4 v154, s[52:53]
	s_mov_b32 m0, s69
	s_add_u32 s38, s54, 0x40000
	global_load_lds_dwordx4 v152, s[52:53]
	s_addc_u32 s39, s55, 0
	s_add_i32 m0, s68, 0x14000
	v_mov_b32_e32 v151, v141
	global_load_lds_dwordx4 v140, s[38:39]
	s_add_i32 m0, s68, 0x16000
	v_mov_b32_e32 v155, v141
	global_load_lds_dwordx4 v150, s[38:39]
	s_add_u32 s38, s52, 0x40000
	s_addc_u32 s39, s53, 0
	s_add_i32 s70, s68, 0x4000
	s_mov_b32 m0, s70
	s_add_i32 s71, s68, 0x6000
	global_load_lds_dwordx4 v154, s[38:39]
	s_mov_b32 m0, s71
	v_mov_b32_e32 v153, v141
	global_load_lds_dwordx4 v152, s[38:39]
	s_load_dwordx2 s[28:29], s[28:29], 0xf8
	s_nop 0
	s_load_dwordx2 s[38:39], s[30:31], 0xf8
	s_nop 0
	s_load_dwordx2 s[30:31], s[34:35], 0xf8
	v_lshl_add_u64 v[6:7], s[54:55], 0, v[140:141]
	v_lshl_add_u64 v[4:5], s[54:55], 0, v[150:151]
	v_lshl_add_u64 v[2:3], s[52:53], 0, v[154:155]
	s_cmp_lg_u32 s6, 0
	v_lshl_add_u64 v[0:1], s[52:53], 0, v[152:153]
	s_cbranch_scc1 .LBB0_239
	s_barrier

my_rs1_7:
	s_or_b64 exec, exec, s[34:35]
	v_readlane_b32 s4, v252, 19
	v_readlane_b32 s5, v252, 20
	s_andn2_b64 vcc, exec, s[4:5]
	s_waitcnt vmcnt(0) lgkmcnt(0)
	s_barrier
	s_cbranch_vccnz .LBB0_301
	v_ashrrev_i32_e32 v1, 31, v8
	v_lshrrev_b32_e32 v1, 26, v1
	v_add_u32_e32 v1, v8, v1
	v_ashrrev_i32_e32 v9, 6, v1
	v_bfe_i32 v1, v8, 27, 1
	v_lshlrev_b32_e32 v0, 4, v8
	v_lshrrev_b32_e32 v1, 22, v1
	v_add_u32_e32 v1, v0, v1
	v_and_b32_e32 v1, 0xfffffc00, v1
	v_sub_u32_e32 v1, v0, v1
	v_lshrrev_b32_e32 v2, 4, v1
	v_bitop3_b32 v2, v2, v1, 32 bitop3:0x6c
	v_ashrrev_i32_e32 v1, 31, v1
	v_lshrrev_b32_e32 v1, 26, v1
	v_add_u32_e32 v1, v2, v1
	v_ashrrev_i32_e32 v10, 6, v1
	v_lshlrev_b32_e32 v3, 3, v9
	v_mul_i32_i24_e32 v4, 64, v10
	v_and_b32_e32 v3, -16, v3
	v_sub_u32_e32 v2, v2, v4
	v_mov_b32_e32 v6, 1
	v_add_u32_e32 v1, v10, v3
	v_lshlrev_b32_e32 v3, 5, v9
	v_ashrrev_i16_sdwa v2, v6, sext(v2) dst_sel:DWORD dst_unused:UNUSED_PAD src0_sel:DWORD src1_sel:BYTE_0
	v_and_b32_e32 v3, 32, v3
	v_bfe_i32 v11, v2, 0, 16
	v_and_b32_e32 v5, 3, v10
	s_mov_b32 s4, 0x1fffe0
	v_add_lshl_u32 v3, v3, v11, 1
	v_add_u32_e32 v0, 0x2000, v0
	v_lshlrev_b32_e32 v2, 1, v1
	v_lshrrev_b32_e32 v4, 2, v1
	v_and_or_b32 v5, v1, s4, v5
	v_lshl_add_u32 v128, v1, 11, v3
	v_ashrrev_i32_e32 v1, 31, v0
	v_lshrrev_b32_e32 v1, 22, v1
	v_add_u32_e32 v1, v0, v1
	v_ashrrev_i32_e32 v12, 10, v1
	v_mul_i32_i24_e32 v1, 0x400, v12
	v_sub_u32_e32 v0, v0, v1
	v_and_b32_e32 v2, 24, v2
	v_and_b32_e32 v4, 4, v4
	v_lshrrev_b32_e32 v1, 4, v0
	v_or3_b32 v2, v5, v4, v2
	v_bitop3_b32 v0, v1, v0, 32 bitop3:0x6c
	v_lshl_add_u32 v140, v2, 11, v3
	v_ashrrev_i32_e32 v2, 31, v0
	s_add_u32 s33, s30, 0x12290000
	v_lshrrev_b32_e32 v2, 26, v2
	s_addc_u32 s41, s31, 0
	v_lshlrev_b32_e32 v1, 3, v12
	v_add_u32_e32 v2, v0, v2
	s_add_u32 s54, s28, 0x1080000
	v_and_b32_e32 v1, -16, v1
	v_ashrrev_i32_e32 v13, 6, v2
	s_addc_u32 s55, s29, 0
	v_add_u32_e32 v1, v13, v1
	v_and_b32_e32 v2, 0xc0, v2
	v_and_b32_e32 v4, 3, v13
	s_ashr_i32 s10, s9, 6
	s_ashr_i32 s6, s9, 8
	v_sub_u32_e32 v0, v0, v2
	v_and_or_b32 v4, v1, s4, v4
	s_lshl_b32 s57, s10, 10
	v_readlane_b32 s4, v253, 47
	v_ashrrev_i16_sdwa v0, v6, sext(v0) dst_sel:DWORD dst_unused:UNUSED_PAD src0_sel:DWORD src1_sel:BYTE_0
	v_readlane_b32 s5, v253, 48
	s_add_u32 s48, s54, s4
	v_lshlrev_b32_e32 v3, 5, v12
	v_bfe_i32 v14, v0, 0, 16
	v_lshlrev_b32_e32 v0, 1, v1
	v_lshrrev_b32_e32 v2, 2, v1
	s_addc_u32 s49, s55, s5
	s_add_i32 s58, s57, 0
	v_and_b32_e32 v3, 32, v3
	v_and_b32_e32 v0, 24, v0
	v_and_b32_e32 v2, 4, v2
	s_add_i32 m0, s58, 0x10000
	v_or3_b32 v0, v4, v2, v0
	v_add_lshl_u32 v2, v3, v14, 1
	global_load_lds_dwordx4 v140, s[48:49]
	s_add_i32 m0, s58, 0x12000
	v_readlane_b32 s4, v253, 62
	v_lshl_add_u32 v132, v0, 11, v2
	v_readlane_b32 s5, v253, 63
	s_add_u32 s4, s33, s4
	global_load_lds_dwordx4 v132, s[48:49]
	s_addc_u32 s5, s41, s5
	s_mov_b32 m0, s58
	s_add_i32 s59, s58, 0x2000
	v_lshl_add_u32 v130, v1, 11, v2
	global_load_lds_dwordx4 v128, s[4:5]
	s_mov_b32 m0, s59
	s_add_u32 s28, s48, 0x40000
	global_load_lds_dwordx4 v130, s[4:5]
	s_addc_u32 s29, s49, 0
	s_add_i32 m0, s58, 0x14000
	v_mov_b32_e32 v133, v141
	global_load_lds_dwordx4 v140, s[28:29]
	s_add_i32 m0, s58, 0x16000
	v_mov_b32_e32 v129, v141
	global_load_lds_dwordx4 v132, s[28:29]
	s_add_u32 s28, s4, 0x40000
	s_addc_u32 s29, s5, 0
	s_add_i32 s68, s58, 0x4000
	s_mov_b32 m0, s68
	s_add_i32 s69, s58, 0x6000
	global_load_lds_dwordx4 v128, s[28:29]
	s_mov_b32 m0, s69
	v_mov_b32_e32 v131, v141
	global_load_lds_dwordx4 v130, s[28:29]
	v_lshl_add_u64 v[6:7], s[48:49], 0, v[140:141]
	v_lshl_add_u64 v[4:5], s[48:49], 0, v[132:133]
	v_lshl_add_u64 v[2:3], s[4:5], 0, v[128:129]
	s_cmp_lg_u32 s6, 0
	v_lshl_add_u64 v[0:1], s[4:5], 0, v[130:131]
	s_cbranch_scc1 .LBB0_290
	s_barrier

.LBB0_304:
	v_ashrrev_i32_e32 v1, 31, v10
	v_lshrrev_b32_e32 v1, 26, v1
	v_add_u32_e32 v1, v10, v1
	v_ashrrev_i32_e32 v8, 6, v1
	v_bfe_i32 v1, v10, 27, 1
	v_lshlrev_b32_e32 v0, 4, v10
	v_lshrrev_b32_e32 v1, 22, v1
	v_add_u32_e32 v1, v0, v1
	v_and_b32_e32 v1, 0xfffffc00, v1
	v_sub_u32_e32 v1, v0, v1
	v_lshrrev_b32_e32 v2, 4, v1
	v_bitop3_b32 v2, v2, v1, 32 bitop3:0x6c
	v_ashrrev_i32_e32 v1, 31, v1
	v_lshrrev_b32_e32 v1, 26, v1
	v_add_u32_e32 v1, v2, v1
	v_ashrrev_i32_e32 v9, 6, v1
	v_lshlrev_b32_e32 v3, 3, v8
	v_mul_i32_i24_e32 v4, 64, v9
	v_and_b32_e32 v3, -16, v3
	v_sub_u32_e32 v2, v2, v4
	v_mov_b32_e32 v6, 1
	s_waitcnt lgkmcnt(0)
	s_add_u32 s33, s28, 0x1d910000
	v_add_u32_e32 v1, v9, v3
	v_lshlrev_b32_e32 v3, 5, v8
	v_ashrrev_i16_sdwa v2, v6, sext(v2) dst_sel:DWORD dst_unused:UNUSED_PAD src0_sel:DWORD src1_sel:BYTE_0
	s_addc_u32 s41, s29, 0
	v_and_b32_e32 v3, 32, v3
	v_bfe_i32 v11, v2, 0, 16
	s_add_u32 s54, s4, 0x1c00000
	v_and_b32_e32 v5, 3, v9
	s_mov_b32 s4, 0x1fffe0
	v_add_lshl_u32 v3, v3, v11, 1
	v_add_u32_e32 v0, 0x2000, v0
	v_lshlrev_b32_e32 v2, 1, v1
	v_lshrrev_b32_e32 v4, 2, v1
	v_and_or_b32 v5, v1, s4, v5
	v_lshl_add_u32 v128, v1, 11, v3
	v_ashrrev_i32_e32 v1, 31, v0
	v_lshrrev_b32_e32 v1, 22, v1
	v_add_u32_e32 v1, v0, v1
	v_ashrrev_i32_e32 v12, 10, v1
	v_mul_i32_i24_e32 v1, 0x400, v12
	v_sub_u32_e32 v0, v0, v1
	v_and_b32_e32 v2, 24, v2
	v_and_b32_e32 v4, 4, v4
	v_lshrrev_b32_e32 v1, 4, v0
	v_or3_b32 v2, v5, v4, v2
	v_bitop3_b32 v0, v1, v0, 32 bitop3:0x6c
	v_lshl_add_u32 v140, v2, 11, v3
	v_ashrrev_i32_e32 v2, 31, v0
	v_lshrrev_b32_e32 v2, 26, v2
	v_lshlrev_b32_e32 v1, 3, v12
	v_add_u32_e32 v2, v0, v2
	v_and_b32_e32 v1, -16, v1
	v_ashrrev_i32_e32 v13, 6, v2
	v_add_u32_e32 v1, v13, v1
	v_and_b32_e32 v4, 3, v13
	v_and_or_b32 v4, v1, s4, v4
	v_readlane_b32 s4, v254, 23
	s_addc_u32 s55, s5, 0
	s_add_i32 s4, s11, s4
	s_ashr_i32 s5, s4, 31
	s_lshr_b32 s5, s5, 27
	s_add_i32 s5, s4, s5
	s_andn2_b32 s5, s5, 31
	s_sub_i32 s4, s4, s5
	s_bfe_i32 s5, s4, 0x80000
	s_bfe_u32 s5, s5, 0x2000d
	s_add_i32 s5, s4, s5
	s_bfe_i32 s11, s5, 0x80000
	s_sext_i32_i16 s11, s11
	s_lshr_b32 s30, s11, 2
	s_and_b32 s5, s5, 0xfffc
	v_and_b32_e32 v2, 0xc0, v2
	s_ashr_i32 s10, s9, 6
	s_sub_i32 s28, s4, s5
	s_bfe_i64 s[34:35], s[30:31], 0x100000
	s_ashr_i32 s6, s9, 8
	v_sub_u32_e32 v0, v0, v2
	s_lshl_b32 s57, s10, 10
	s_bfe_i64 s[4:5], s[28:29], 0x80000
	s_lshl_b64 s[34:35], s[34:35], 19
	v_ashrrev_i16_sdwa v0, v6, sext(v0) dst_sel:DWORD dst_unused:UNUSED_PAD src0_sel:DWORD src1_sel:BYTE_0
	s_add_u32 s48, s54, s34
	v_lshlrev_b32_e32 v3, 5, v12
	v_bfe_i32 v14, v0, 0, 16
	v_lshlrev_b32_e32 v0, 1, v1
	v_lshrrev_b32_e32 v2, 2, v1
	s_addc_u32 s49, s55, s35
	s_add_i32 s58, s57, 0
	v_and_b32_e32 v3, 32, v3
	v_and_b32_e32 v0, 24, v0
	v_and_b32_e32 v2, 4, v2
	s_add_i32 m0, s58, 0x10000
	v_or3_b32 v0, v4, v2, v0
	v_add_lshl_u32 v2, v3, v14, 1
	global_load_lds_dwordx4 v140, s[48:49]
	s_add_i32 m0, s58, 0x12000
	s_lshl_b64 s[4:5], s[4:5], 19
	v_lshl_add_u32 v132, v0, 11, v2
	s_add_u32 s4, s33, s4
	global_load_lds_dwordx4 v132, s[48:49]
	s_addc_u32 s5, s41, s5
	s_mov_b32 m0, s58
	s_add_i32 s59, s58, 0x2000
	v_lshl_add_u32 v130, v1, 11, v2
	global_load_lds_dwordx4 v128, s[4:5]
	s_mov_b32 m0, s59
	s_add_u32 s34, s48, 0x40000
	global_load_lds_dwordx4 v130, s[4:5]
	s_addc_u32 s35, s49, 0
	s_add_i32 m0, s58, 0x14000
	v_mov_b32_e32 v133, v141
	global_load_lds_dwordx4 v140, s[34:35]
	s_add_i32 m0, s58, 0x16000
	v_mov_b32_e32 v129, v141
	global_load_lds_dwordx4 v132, s[34:35]
	s_add_u32 s34, s4, 0x40000
	s_addc_u32 s35, s5, 0
	s_add_i32 s68, s58, 0x4000
	s_mov_b32 m0, s68
	s_add_i32 s69, s58, 0x6000
	global_load_lds_dwordx4 v128, s[34:35]
	s_mov_b32 m0, s69
	v_mov_b32_e32 v131, v141
	global_load_lds_dwordx4 v130, s[34:35]
	v_lshl_add_u64 v[6:7], s[48:49], 0, v[140:141]
	v_lshl_add_u64 v[4:5], s[48:49], 0, v[132:133]
	v_lshl_add_u64 v[2:3], s[4:5], 0, v[128:129]
	s_cmp_lg_u32 s6, 0
	v_lshl_add_u64 v[0:1], s[4:5], 0, v[130:131]
	s_cbranch_scc1 .LBB0_306
	s_barrier

.LBB0_323:
	s_and_b64 vcc, exec, s[26:27]
	s_cbranch_vccz .LBB0_358
	s_cmp_lt_i32 s60, 5
	s_cbranch_scc0 .LBB0_358
	v_readlane_b32 s10, v252, 17
	s_mov_b64 s[38:39], s[0:1]
	s_mov_b64 s[34:35], s[0:1]
	s_mov_b64 s[26:27], s[0:1]
	s_mov_b64 s[28:29], s[0:1]
	s_mov_b64 s[30:31], s[0:1]
	v_mov_b32_e32 v8, v186
	v_readlane_b32 s11, v252, 18
	s_andn2_b64 vcc, exec, s[10:11]
	v_readfirstlane_b32 s9, v8
	s_cbranch_vccnz .LBB0_443
	v_lshlrev_b32_e32 v0, 4, v8
	s_waitcnt lgkmcnt(0)
	v_add_u32_e32 v1, 0x2000, v0
	v_ashrrev_i32_e32 v2, 31, v1
	v_lshrrev_b32_e32 v2, 22, v2
	v_add_u32_e32 v2, v1, v2
	v_ashrrev_i32_e32 v9, 10, v2
	v_mul_i32_i24_e32 v2, 0x400, v9
	v_sub_u32_e32 v1, v1, v2
	v_lshrrev_b32_e32 v2, 4, v1
	v_bitop3_b32 v1, v2, v1, 32 bitop3:0x6c
	v_ashrrev_i32_e32 v2, 31, v1
	v_lshrrev_b32_e32 v2, 26, v2
	v_add_u32_e32 v2, v1, v2
	v_lshlrev_b32_e32 v3, 3, v9
	v_ashrrev_i32_e32 v10, 6, v2
	v_and_b32_e32 v3, -16, v3
	v_add_u32_e32 v3, v10, v3
	s_load_dwordx2 s[10:11], s[38:39], 0xf8
	s_nop 0
	s_load_dwordx2 s[34:35], s[34:35], 0xf8
	v_and_b32_e32 v4, 3, v10
	s_mov_b32 s12, 0xffffe0
	v_lshrrev_b32_e32 v5, 2, v3
	v_lshlrev_b32_e32 v6, 1, v3
	v_and_or_b32 v4, v3, s12, v4
	v_and_b32_e32 v5, 4, v5
	v_and_b32_e32 v6, 24, v6
	v_or3_b32 v4, v4, v5, v6
	v_lshlrev_b32_e32 v5, 5, v9
	v_and_b32_e32 v2, 0xc0, v2
	v_and_b32_e32 v11, 32, v5
	v_sub_u32_e32 v1, v1, v2
	v_mov_b32_e32 v5, 1
	s_waitcnt lgkmcnt(0)
	s_add_u32 s33, s10, 0x3290000
	v_ashrrev_i16_sdwa v1, v5, sext(v1) dst_sel:DWORD dst_unused:UNUSED_PAD src0_sel:DWORD src1_sel:BYTE_0
	s_addc_u32 s41, s11, 0
	v_bfe_i32 v12, v1, 0, 16
	s_movk_i32 s11, 0xb00
	v_mul_u32_u24_e32 v4, 0xb00, v4
	v_add_u32_e32 v1, v11, v12
	v_mul_lo_u32 v2, v3, s11
	v_add_lshl_u32 v150, v4, v1, 1
	v_add_lshl_u32 v152, v1, v2, 1
	v_bfe_i32 v1, v8, 27, 1
	v_lshrrev_b32_e32 v1, 22, v1
	v_add_u32_e32 v1, v0, v1
	v_and_b32_e32 v1, 0xfffffc00, v1
	v_sub_u32_e32 v0, v0, v1
	v_lshrrev_b32_e32 v1, 4, v0
	v_bitop3_b32 v1, v1, v0, 32 bitop3:0x6c
	v_ashrrev_i32_e32 v0, 31, v0
	v_lshrrev_b32_e32 v0, 26, v0
	v_add_u32_e32 v0, v1, v0
	v_ashrrev_i32_e32 v13, 6, v0
	v_ashrrev_i32_e32 v0, 31, v8
	v_lshrrev_b32_e32 v0, 26, v0
	v_add_u32_e32 v0, v8, v0
	v_ashrrev_i32_e32 v14, 6, v0
	v_lshlrev_b32_e32 v0, 3, v14
	v_and_b32_e32 v0, -16, v0
	v_add_u32_e32 v0, v13, v0
	v_and_b32_e32 v2, 3, v13
	v_lshrrev_b32_e32 v3, 2, v0
	v_lshlrev_b32_e32 v4, 1, v0
	v_and_or_b32 v2, v0, s12, v2
	v_and_b32_e32 v3, 4, v3
	v_and_b32_e32 v4, 24, v4
	v_or3_b32 v2, v2, v3, v4
	v_lshlrev_b32_e32 v3, 5, v14
	s_add_u32 s54, s34, 0xb00000
	v_and_b32_e32 v15, 32, v3
	v_mul_i32_i24_e32 v3, 64, v13
	s_addc_u32 s55, s35, 0
	s_ashr_i32 s10, s9, 6
	v_sub_u32_e32 v1, v1, v3
	s_ashr_i32 s6, s9, 8
	s_lshl_b32 s57, s10, 10
	v_ashrrev_i16_sdwa v1, v5, sext(v1) dst_sel:DWORD dst_unused:UNUSED_PAD src0_sel:DWORD src1_sel:BYTE_0
	v_mul_lo_u32 v0, v0, s11
	v_readlane_b32 s11, v254, 53
	v_bfe_i32 v16, v1, 0, 16
	s_add_u32 s52, s54, s11
	v_readlane_b32 s11, v254, 51
	v_mul_u32_u24_e32 v2, 0xb00, v2
	v_add_u32_e32 v1, v15, v16
	s_addc_u32 s53, s55, s11
	s_add_i32 s58, s57, 0
	v_add_lshl_u32 v140, v2, v1, 1
	s_add_i32 m0, s58, 0x10000
	v_readlane_b32 s11, v254, 57
	global_load_lds_dwordx4 v140, s[52:53]
	s_add_i32 m0, s58, 0x12000
	s_add_u32 s50, s33, s11
	v_readlane_b32 s11, v254, 54
	v_add_lshl_u32 v154, v1, v0, 1
	global_load_lds_dwordx4 v150, s[52:53]
	s_addc_u32 s51, s41, s11
	s_mov_b32 m0, s58
	s_add_i32 s59, s58, 0x2000
	global_load_lds_dwordx4 v154, s[50:51]
	s_mov_b32 m0, s59
	s_add_u32 s34, s52, 0xb0000
	global_load_lds_dwordx4 v152, s[50:51]
	s_addc_u32 s35, s53, 0
	s_add_i32 m0, s58, 0x14000
	v_mov_b32_e32 v151, v141
	global_load_lds_dwordx4 v140, s[34:35]
	s_add_i32 m0, s58, 0x16000
	v_mov_b32_e32 v155, v141
	global_load_lds_dwordx4 v150, s[34:35]
	s_add_u32 s34, s50, 0xb0000
	s_addc_u32 s35, s51, 0
	s_add_i32 s68, s58, 0x4000
	s_mov_b32 m0, s68
	s_add_i32 s69, s58, 0x6000
	global_load_lds_dwordx4 v154, s[34:35]
	s_mov_b32 m0, s69
	v_mov_b32_e32 v153, v141
	global_load_lds_dwordx4 v152, s[34:35]
	s_load_dwordx2 s[26:27], s[26:27], 0xf8
	s_nop 0
	s_load_dwordx2 s[34:35], s[28:29], 0xf8
	s_nop 0
	s_load_dwordx2 s[28:29], s[30:31], 0xf8
	v_lshl_add_u64 v[6:7], s[52:53], 0, v[140:141]
	v_lshl_add_u64 v[4:5], s[52:53], 0, v[150:151]
	v_lshl_add_u64 v[2:3], s[50:51], 0, v[154:155]
	s_cmp_lg_u32 s6, 0
	v_lshl_add_u64 v[0:1], s[50:51], 0, v[152:153]
	s_cbranch_scc1 .LBB0_328
	s_barrier

my_rs2_7:
	s_or_b64 exec, exec, s[38:39]
	v_readlane_b32 s10, v252, 21
	v_readlane_b32 s11, v252, 22
	s_andn2_b64 vcc, exec, s[10:11]
	s_waitcnt vmcnt(0) lgkmcnt(0)
	s_barrier
	s_cbranch_vccnz .LBB0_392
	v_ashrrev_i32_e32 v1, 31, v8
	v_lshrrev_b32_e32 v1, 26, v1
	v_add_u32_e32 v1, v8, v1
	v_ashrrev_i32_e32 v9, 6, v1
	v_bfe_i32 v1, v8, 27, 1
	v_lshlrev_b32_e32 v0, 4, v8
	v_lshrrev_b32_e32 v1, 22, v1
	v_add_u32_e32 v1, v0, v1
	v_and_b32_e32 v1, 0xfffffc00, v1
	v_sub_u32_e32 v1, v0, v1
	v_lshrrev_b32_e32 v2, 4, v1
	v_bitop3_b32 v2, v2, v1, 32 bitop3:0x6c
	v_ashrrev_i32_e32 v1, 31, v1
	v_lshrrev_b32_e32 v1, 26, v1
	v_add_u32_e32 v1, v2, v1
	v_ashrrev_i32_e32 v10, 6, v1
	v_lshlrev_b32_e32 v3, 3, v9
	v_mul_i32_i24_e32 v4, 64, v10
	v_and_b32_e32 v3, -16, v3
	v_sub_u32_e32 v2, v2, v4
	v_mov_b32_e32 v6, 1
	v_add_u32_e32 v1, v10, v3
	v_lshlrev_b32_e32 v3, 5, v9
	v_ashrrev_i16_sdwa v2, v6, sext(v2) dst_sel:DWORD dst_unused:UNUSED_PAD src0_sel:DWORD src1_sel:BYTE_0
	v_and_b32_e32 v3, 32, v3
	v_bfe_i32 v11, v2, 0, 16
	v_and_b32_e32 v5, 3, v10
	s_mov_b32 s10, 0x1fffe0
	v_add_lshl_u32 v3, v3, v11, 1
	v_add_u32_e32 v0, 0x2000, v0
	v_lshlrev_b32_e32 v2, 1, v1
	v_lshrrev_b32_e32 v4, 2, v1
	v_and_or_b32 v5, v1, s10, v5
	v_lshl_add_u32 v128, v1, 11, v3
	v_ashrrev_i32_e32 v1, 31, v0
	v_lshrrev_b32_e32 v1, 22, v1
	v_add_u32_e32 v1, v0, v1
	v_ashrrev_i32_e32 v12, 10, v1
	v_mul_i32_i24_e32 v1, 0x400, v12
	v_sub_u32_e32 v0, v0, v1
	v_and_b32_e32 v2, 24, v2
	v_and_b32_e32 v4, 4, v4
	v_lshrrev_b32_e32 v1, 4, v0
	v_or3_b32 v2, v5, v4, v2
	v_bitop3_b32 v0, v1, v0, 32 bitop3:0x6c
	v_lshl_add_u32 v140, v2, 11, v3
	v_ashrrev_i32_e32 v2, 31, v0
	v_lshrrev_b32_e32 v2, 26, v2
	v_lshlrev_b32_e32 v1, 3, v12
	v_add_u32_e32 v2, v0, v2
	v_and_b32_e32 v1, -16, v1
	v_ashrrev_i32_e32 v13, 6, v2
	s_add_u32 s33, s34, 0x12290000
	v_add_u32_e32 v1, v13, v1
	v_and_b32_e32 v4, 3, v13
	s_addc_u32 s41, s35, 0
	v_and_b32_e32 v2, 0xc0, v2
	v_and_or_b32 v4, v1, s10, v4
	s_ashr_i32 s10, s9, 6
	s_ashr_i32 s6, s9, 8
	v_sub_u32_e32 v0, v0, v2
	s_lshl_b32 s57, s10, 10
	v_readlane_b32 s28, v253, 50
	v_ashrrev_i16_sdwa v0, v6, sext(v0) dst_sel:DWORD dst_unused:UNUSED_PAD src0_sel:DWORD src1_sel:BYTE_0
	v_readlane_b32 s29, v253, 51
	s_add_u32 s52, s26, s28
	v_lshlrev_b32_e32 v3, 5, v12
	v_bfe_i32 v14, v0, 0, 16
	v_lshlrev_b32_e32 v0, 1, v1
	v_lshrrev_b32_e32 v2, 2, v1
	s_addc_u32 s53, s27, s29
	s_add_i32 s68, s57, 0
	v_and_b32_e32 v3, 32, v3
	v_and_b32_e32 v0, 24, v0
	v_and_b32_e32 v2, 4, v2
	s_add_i32 m0, s68, 0x10000
	v_or3_b32 v0, v4, v2, v0
	v_add_lshl_u32 v2, v3, v14, 1
	global_load_lds_dwordx4 v140, s[52:53]
	s_add_i32 m0, s68, 0x12000
	v_readlane_b32 s28, v254, 2
	v_lshl_add_u32 v132, v0, 11, v2
	v_readlane_b32 s29, v254, 3
	s_add_u32 s28, s33, s28
	global_load_lds_dwordx4 v132, s[52:53]
	s_addc_u32 s29, s41, s29
	s_mov_b32 m0, s68
	s_add_i32 s69, s68, 0x2000
	v_lshl_add_u32 v130, v1, 11, v2
	global_load_lds_dwordx4 v128, s[28:29]
	s_mov_b32 m0, s69
	s_add_u32 s34, s52, 0x40000
	global_load_lds_dwordx4 v130, s[28:29]
	s_addc_u32 s35, s53, 0
	s_add_i32 m0, s68, 0x14000
	v_mov_b32_e32 v133, v141
	global_load_lds_dwordx4 v140, s[34:35]
	s_add_i32 m0, s68, 0x16000
	v_mov_b32_e32 v129, v141
	global_load_lds_dwordx4 v132, s[34:35]
	s_add_u32 s34, s28, 0x40000
	s_addc_u32 s35, s29, 0
	s_add_i32 s70, s68, 0x4000
	s_mov_b32 m0, s70
	s_add_i32 s71, s68, 0x6000
	global_load_lds_dwordx4 v128, s[34:35]
	s_mov_b32 m0, s71
	v_mov_b32_e32 v131, v141
	global_load_lds_dwordx4 v130, s[34:35]
	v_lshl_add_u64 v[6:7], s[52:53], 0, v[140:141]
	v_lshl_add_u64 v[4:5], s[52:53], 0, v[132:133]
	v_lshl_add_u64 v[2:3], s[28:29], 0, v[128:129]
	s_cmp_lg_u32 s6, 0
	v_lshl_add_u64 v[0:1], s[28:29], 0, v[130:131]
	s_cbranch_scc1 .LBB0_381
	s_barrier

.LBB0_757:
	v_readlane_b32 s10, v252, 31
	s_mov_b64 s[26:27], s[0:1]
	s_mov_b64 s[4:5], s[0:1]
	s_mov_b64 s[28:29], s[0:1]
	v_mov_b32_e32 v8, v186
	v_readlane_b32 s11, v252, 32
	s_and_b64 vcc, exec, s[10:11]
	v_readfirstlane_b32 s9, v8
	s_cbranch_vccz .LBB0_779
	v_lshlrev_b32_e32 v0, 4, v8
	v_add_u32_e32 v1, 0x2000, v0
	v_ashrrev_i32_e32 v2, 31, v1
	v_lshrrev_b32_e32 v2, 22, v2
	v_add_u32_e32 v2, v1, v2
	v_ashrrev_i32_e32 v2, 10, v2
	v_mul_i32_i24_e32 v3, 0x400, v2
	v_sub_u32_e32 v1, v1, v3
	v_lshrrev_b32_e32 v3, 4, v1
	s_load_dwordx2 s[10:11], s[26:27], 0xf8
	s_nop 0
	s_load_dwordx2 s[4:5], s[4:5], 0xf8
	v_bitop3_b32 v1, v3, v1, 32 bitop3:0x6c
	v_ashrrev_i32_e32 v3, 31, v1
	v_lshrrev_b32_e32 v3, 26, v3
	v_add_u32_e32 v3, v1, v3
	v_lshlrev_b32_e32 v5, 3, v2
	s_waitcnt lgkmcnt(0)
	s_add_u32 s33, s10, 0x1db10000
	v_ashrrev_i32_e32 v4, 6, v3
	v_and_b32_e32 v5, -16, v5
	s_addc_u32 s41, s11, 0
	v_add_u32_e32 v5, v4, v5
	s_add_u32 s57, s4, 0x1a00000
	v_and_b32_e32 v4, 3, v4
	s_mov_b32 s4, 0x1fffe0
	v_lshrrev_b32_e32 v6, 2, v5
	v_lshlrev_b32_e32 v7, 1, v5
	v_and_or_b32 v4, v5, s4, v4
	v_and_b32_e32 v6, 4, v6
	v_and_b32_e32 v7, 24, v7
	v_and_b32_e32 v3, 0xc0, v3
	v_or3_b32 v4, v4, v6, v7
	v_sub_u32_e32 v1, v1, v3
	v_mov_b32_e32 v7, 1
	v_lshlrev_b32_e32 v2, 5, v2
	v_ashrrev_i16_sdwa v1, v7, sext(v1) dst_sel:DWORD dst_unused:UNUSED_PAD src0_sel:DWORD src1_sel:BYTE_0
	v_and_b32_e32 v2, 32, v2
	v_bfe_i32 v1, v1, 0, 16
	v_add_lshl_u32 v1, v2, v1, 1
	v_lshl_add_u32 v128, v4, 11, v1
	v_lshl_add_u32 v130, v5, 12, v1
	v_bfe_i32 v1, v8, 27, 1
	v_lshrrev_b32_e32 v1, 22, v1
	v_add_u32_e32 v1, v0, v1
	v_and_b32_e32 v1, 0xfffffc00, v1
	v_sub_u32_e32 v0, v0, v1
	v_ashrrev_i32_e32 v2, 31, v8
	v_lshrrev_b32_e32 v1, 4, v0
	v_lshrrev_b32_e32 v2, 26, v2
	v_bitop3_b32 v1, v1, v0, 32 bitop3:0x6c
	v_ashrrev_i32_e32 v0, 31, v0
	v_add_u32_e32 v2, v8, v2
	v_lshrrev_b32_e32 v0, 26, v0
	v_ashrrev_i32_e32 v2, 6, v2
	v_add_u32_e32 v0, v1, v0
	v_lshlrev_b32_e32 v3, 3, v2
	s_addc_u32 s60, s5, 0
	s_ashr_i32 s6, s9, 6
	v_ashrrev_i32_e32 v0, 6, v0
	v_and_b32_e32 v3, -16, v3
	s_ashr_i32 s10, s9, 8
	s_lshl_b32 s68, s6, 10
	v_add_u32_e32 v3, v0, v3
	v_and_b32_e32 v4, 3, v0
	v_mul_i32_i24_e32 v0, 64, v0
	v_readlane_b32 s19, v254, 50
	v_and_or_b32 v4, v3, s4, v4
	v_sub_u32_e32 v0, v1, v0
	s_add_u32 s4, s57, s19
	v_lshrrev_b32_e32 v5, 2, v3
	v_lshlrev_b32_e32 v6, 1, v3
	v_lshlrev_b32_e32 v2, 5, v2
	v_ashrrev_i16_sdwa v0, v7, sext(v0) dst_sel:DWORD dst_unused:UNUSED_PAD src0_sel:DWORD src1_sel:BYTE_0
	s_addc_u32 s5, s60, 0
	v_readlane_b32 s26, v254, 6
	v_and_b32_e32 v5, 4, v5
	v_and_b32_e32 v6, 24, v6
	v_and_b32_e32 v2, 32, v2
	v_bfe_i32 v0, v0, 0, 16
	v_readlane_b32 s27, v254, 7
	s_add_u32 s4, s4, s26
	v_or3_b32 v4, v4, v5, v6
	v_add_lshl_u32 v0, v2, v0, 1
	s_addc_u32 s5, s5, s27
	s_add_i32 s69, s68, 0
	v_lshl_add_u32 v140, v4, 11, v0
	s_add_i32 m0, s69, 0x10000
	v_readlane_b32 s26, v253, 53
	global_load_lds_dwordx4 v140, s[4:5]
	s_add_i32 m0, s69, 0x12000
	v_readlane_b32 s27, v253, 54
	s_add_u32 s11, s33, s26
	s_addc_u32 s12, s41, s27
	s_add_u32 s26, s11, s19
	v_lshl_add_u32 v132, v3, 12, v0
	global_load_lds_dwordx4 v128, s[4:5]
	s_addc_u32 s27, s12, 0
	s_mov_b32 m0, s69
	s_add_i32 s70, s69, 0x2000
	global_load_lds_dwordx4 v132, s[26:27]
	s_mov_b32 m0, s70
	s_add_u32 s30, s4, 0x40000
	global_load_lds_dwordx4 v130, s[26:27]
	s_addc_u32 s31, s5, 0
	s_add_i32 m0, s69, 0x14000
	s_load_dwordx2 s[28:29], s[28:29], 0xf8
	global_load_lds_dwordx4 v140, s[30:31]
	s_add_i32 m0, s69, 0x16000
	v_mov_b32_e32 v129, v141
	global_load_lds_dwordx4 v128, s[30:31]
	s_add_u32 s30, s26, 0x80000
	s_addc_u32 s31, s27, 0
	s_add_i32 s71, s69, 0x4000
	s_mov_b32 m0, s71
	s_add_i32 s72, s69, 0x6000
	global_load_lds_dwordx4 v132, s[30:31]
	s_mov_b32 m0, s72
	v_mov_b32_e32 v133, v141
	global_load_lds_dwordx4 v130, s[30:31]
	v_mov_b32_e32 v131, v141
	v_lshl_add_u64 v[6:7], s[4:5], 0, v[140:141]
	v_lshl_add_u64 v[4:5], s[4:5], 0, v[128:129]
	v_lshl_add_u64 v[2:3], s[26:27], 0, v[132:133]
	s_cmp_lg_u32 s10, 0
	v_lshl_add_u64 v[0:1], s[26:27], 0, v[130:131]
	s_cbranch_scc1 .LBB0_760
	s_barrier

.LBB0_782:
	v_bfe_i32 v2, v8, 27, 1
	v_lshlrev_b32_e32 v0, 4, v8
	v_lshrrev_b32_e32 v2, 22, v2
	v_add_u32_e32 v2, v0, v2
	v_and_b32_e32 v2, 0xfffffc00, v2
	v_sub_u32_e32 v2, v0, v2
	v_ashrrev_i32_e32 v1, 31, v8
	v_lshrrev_b32_e32 v3, 4, v2
	v_lshrrev_b32_e32 v1, 26, v1
	v_bitop3_b32 v3, v3, v2, 32 bitop3:0x6c
	v_ashrrev_i32_e32 v2, 31, v2
	v_add_u32_e32 v1, v8, v1
	v_lshrrev_b32_e32 v2, 26, v2
	v_ashrrev_i32_e32 v1, 6, v1
	v_add_u32_e32 v2, v3, v2
	v_lshlrev_b32_e32 v4, 3, v1
	v_ashrrev_i32_e32 v2, 6, v2
	s_waitcnt lgkmcnt(0)
	s_add_u32 s33, s34, 0x2000000
	v_and_b32_e32 v4, -16, v4
	v_mul_i32_i24_e32 v5, 64, v2
	s_addc_u32 s41, s35, 0
	v_add_u32_e32 v4, v2, v4
	v_sub_u32_e32 v3, v3, v5
	v_mov_b32_e32 v7, 1
	s_add_u32 s57, s4, 0x1db10800
	v_lshlrev_b32_e32 v1, 5, v1
	v_ashrrev_i16_sdwa v3, v7, sext(v3) dst_sel:DWORD dst_unused:UNUSED_PAD src0_sel:DWORD src1_sel:BYTE_0
	v_lshlrev_b32_e32 v5, 1, v4
	v_lshrrev_b32_e32 v6, 2, v4
	v_and_b32_e32 v2, 3, v2
	s_mov_b32 s4, 0xfffe0
	v_and_b32_e32 v1, 32, v1
	v_bfe_i32 v3, v3, 0, 16
	v_and_b32_e32 v5, 24, v5
	v_and_b32_e32 v6, 4, v6
	v_and_or_b32 v2, v4, s4, v2
	v_or3_b32 v2, v2, v6, v5
	v_add_lshl_u32 v1, v1, v3, 1
	v_add_u32_e32 v0, 0x2000, v0
	v_lshl_add_u32 v128, v4, 11, v1
	v_lshl_add_u32 v130, v2, 12, v1
	v_ashrrev_i32_e32 v1, 31, v0
	v_lshrrev_b32_e32 v1, 22, v1
	v_add_u32_e32 v1, v0, v1
	v_ashrrev_i32_e32 v1, 10, v1
	v_mul_i32_i24_e32 v2, 0x400, v1
	v_sub_u32_e32 v0, v0, v2
	v_lshrrev_b32_e32 v2, 4, v0
	v_bitop3_b32 v0, v2, v0, 32 bitop3:0x6c
	v_ashrrev_i32_e32 v3, 31, v0
	v_lshrrev_b32_e32 v3, 26, v3
	v_lshlrev_b32_e32 v2, 3, v1
	v_add_u32_e32 v3, v0, v3
	v_and_b32_e32 v2, -16, v2
	v_ashrrev_i32_e32 v4, 6, v3
	v_add_u32_e32 v2, v4, v2
	v_and_b32_e32 v4, 3, v4
	v_and_or_b32 v4, v2, s4, v4
	v_readlane_b32 s4, v254, 31
	s_addc_u32 s60, s5, 0
	s_add_i32 s4, s11, s4
	s_ashr_i32 s5, s4, 31
	s_lshr_b32 s5, s5, 30
	s_add_i32 s5, s4, s5
	s_and_b32 s11, s5, -4
	s_ashr_i32 s26, s5, 4
	s_ashr_i32 s10, s9, 6
	s_sub_i32 s4, s4, s11
	s_ashr_i32 s27, s26, 31
	s_ashr_i32 s6, s9, 8
	s_lshl_b32 s70, s10, 10
	s_ashr_i32 s71, s5, 2
	s_ashr_i32 s5, s4, 31
	s_lshl_b64 s[26:27], s[26:27], 20
	s_add_u32 s11, s57, s26
	s_addc_u32 s12, s60, s27
	s_lshl_b32 s19, s71, 9
	s_and_b32 s19, s19, 0x600
	s_add_u32 s26, s11, s19
	v_and_b32_e32 v3, 0xc0, v3
	s_addc_u32 s27, s12, 0
	s_add_i32 s72, s70, 0
	v_sub_u32_e32 v0, v0, v3
	s_add_i32 m0, s72, 0x10000
	v_lshlrev_b32_e32 v1, 5, v1
	v_ashrrev_i16_sdwa v0, v7, sext(v0) dst_sel:DWORD dst_unused:UNUSED_PAD src0_sel:DWORD src1_sel:BYTE_0
	v_lshlrev_b32_e32 v3, 1, v2
	v_lshrrev_b32_e32 v5, 2, v2
	global_load_lds_dwordx4 v130, s[26:27]
	s_add_i32 m0, s72, 0x12000
	v_and_b32_e32 v1, 32, v1
	v_bfe_i32 v0, v0, 0, 16
	v_and_b32_e32 v3, 24, v3
	v_and_b32_e32 v5, 4, v5
	s_add_u32 s11, s33, s19
	v_or3_b32 v3, v4, v5, v3
	v_add_lshl_u32 v0, v1, v0, 1
	s_addc_u32 s12, s41, 0
	s_lshl_b64 s[28:29], s[4:5], 19
	v_lshl_add_u32 v134, v3, 12, v0
	s_add_u32 s28, s11, s28
	global_load_lds_dwordx4 v134, s[26:27]
	s_addc_u32 s29, s12, s29
	s_mov_b32 m0, s72
	s_add_i32 s73, s72, 0x2000
	v_lshl_add_u32 v132, v2, 11, v0
	global_load_lds_dwordx4 v128, s[28:29]
	s_mov_b32 m0, s73
	s_add_u32 s34, s26, 0x80000
	global_load_lds_dwordx4 v132, s[28:29]
	s_addc_u32 s35, s27, 0
	s_add_i32 m0, s72, 0x14000
	v_mov_b32_e32 v131, v141
	global_load_lds_dwordx4 v130, s[34:35]
	s_add_i32 m0, s72, 0x16000
	v_mov_b32_e32 v135, v141
	global_load_lds_dwordx4 v134, s[34:35]
	s_add_u32 s34, s28, 0x40000
	s_addc_u32 s35, s29, 0
	s_add_i32 s74, s72, 0x4000
	s_mov_b32 m0, s74
	s_add_i32 s75, s72, 0x6000
	global_load_lds_dwordx4 v128, s[34:35]
	s_mov_b32 m0, s75
	v_mov_b32_e32 v129, v141
	global_load_lds_dwordx4 v132, s[34:35]
	v_mov_b32_e32 v133, v141
	v_lshl_add_u64 v[6:7], s[26:27], 0, v[130:131]
	v_lshl_add_u64 v[4:5], s[26:27], 0, v[134:135]
	v_lshl_add_u64 v[2:3], s[28:29], 0, v[128:129]
	s_cmp_lg_u32 s6, 0
	v_lshl_add_u64 v[0:1], s[28:29], 0, v[132:133]
	s_cbranch_scc1 .LBB0_784
	s_barrier
